# strategy 4 on the FFN-in GEMM body: one static s_setprio 1 for the trailing wave half, per-section priority flips removed (on v52)
# baseline (speedup 1.0000x reference)
.LBB0_477:
	s_ashr_i32 s17, s16, 31
	s_lshl_b64 s[18:19], s[16:17], 19
	s_add_u32 s18, s0, s18
	s_addc_u32 s19, s1, s19
	s_and_b64 s[24:25], s[38:39], exec
	s_cselect_b32 s4, s19, s41
	s_cselect_b32 s9, s18, s40
	s_ashr_i32 s85, s84, 31
	s_lshl_b64 s[24:25], s[84:85], 19
	s_add_u32 s82, s80, s24
	s_addc_u32 s83, s81, s25
	s_and_b64 s[24:25], s[38:39], exec
	s_cselect_b32 s17, s83, s13
	s_cselect_b32 s24, s82, s12
	s_add_u32 s40, s40, 0x40080
	s_addc_u32 s41, s41, 0
	s_add_u32 s25, s12, 0x100
	s_addc_u32 s50, s13, 0
	s_mov_b32 s51, -2
	s_cmp_lg_u32 s90, 0
	s_cbranch_scc0 .Lsp_skip
	s_setprio 1
.Lsp_skip:
	s_add_u32 s12, s40, 0xfffc0080
	s_addc_u32 s13, s41, -1
	s_add_i32 s85, 0, 0x10000
	s_cmp_eq_u32 s51, 12
	s_cselect_b32 s43, s4, s13
	s_cselect_b32 s42, s9, s12
	v_add_u32_e32 v158, s85, v196
	s_cselect_b32 s13, s17, s50
	s_cselect_b32 s12, s24, s25
	s_add_i32 s27, 0, 0x14000
	ds_read_b128 v[150:153], v158
	ds_read_b128 v[154:157], v158 offset:1024
	ds_read_b128 v[170:173], v158 offset:2048
	ds_read_b128 v[174:177], v158 offset:3072
	v_add_u32_e32 v158, s27, v196
	ds_read_b128 v[178:181], v158
	ds_read_b128 v[182:185], v158 offset:1024
	ds_read_b128 v[186:189], v158 offset:2048
	ds_read_b128 v[200:203], v158 offset:3072
	s_add_i32 m0, s15, 0xc000
	ds_read_b128 v[204:207], v199
	ds_read_b128 v[208:211], v199 offset:1024
	ds_read_b128 v[212:215], v199 offset:2048
	ds_read_b128 v[234:237], v199 offset:3072
	ds_read_b128 v[238:241], v199 offset:4096
	ds_read_b128 v[242:245], v199 offset:5120
	ds_read_b128 v[246:249], v199 offset:6144
	ds_read_b128 v[222:225], v199 offset:7168
	global_load_lds_dwordx4 v146, s[40:41]
	s_add_i32 m0, s15, 0xe000
	s_nop 0
	global_load_lds_dwordx4 v148, s[40:41]
	s_waitcnt vmcnt(8)
	s_waitcnt lgkmcnt(0)
	s_barrier
	s_waitcnt lgkmcnt(0)
	v_mfma_f32_16x16x32_bf16 v[124:127], v[150:153], v[204:207], 0
	v_mfma_f32_16x16x32_bf16 v[120:123], v[170:173], v[204:207], 0
	v_mfma_f32_16x16x32_bf16 v[108:111], v[150:153], v[212:215], 0
	v_mfma_f32_16x16x32_bf16 v[104:107], v[170:173], v[212:215], 0
	v_mfma_f32_16x16x32_bf16 v[92:95], v[150:153], v[238:241], 0
	v_mfma_f32_16x16x32_bf16 v[88:91], v[170:173], v[238:241], 0
	v_mfma_f32_16x16x32_bf16 v[76:79], v[150:153], v[246:249], 0
	v_mfma_f32_16x16x32_bf16 v[72:75], v[170:173], v[246:249], 0
	v_mfma_f32_16x16x32_bf16 v[124:127], v[154:157], v[208:211], v[124:127]
	v_mfma_f32_16x16x32_bf16 v[120:123], v[174:177], v[208:211], v[120:123]
	v_mfma_f32_16x16x32_bf16 v[108:111], v[154:157], v[234:237], v[108:111]
	v_mfma_f32_16x16x32_bf16 v[104:107], v[174:177], v[234:237], v[104:107]
	v_mfma_f32_16x16x32_bf16 v[92:95], v[154:157], v[242:245], v[92:95]
	v_mfma_f32_16x16x32_bf16 v[88:91], v[174:177], v[242:245], v[88:91]
	v_mfma_f32_16x16x32_bf16 v[76:79], v[154:157], v[222:225], v[76:79]
	v_mfma_f32_16x16x32_bf16 v[72:75], v[174:177], v[222:225], v[72:75]
	v_mfma_f32_16x16x32_bf16 v[116:119], v[178:181], v[204:207], 0
	v_mfma_f32_16x16x32_bf16 v[112:115], v[186:189], v[204:207], 0
	v_mfma_f32_16x16x32_bf16 v[100:103], v[178:181], v[212:215], 0
	v_mfma_f32_16x16x32_bf16 v[96:99], v[186:189], v[212:215], 0
	v_mfma_f32_16x16x32_bf16 v[84:87], v[178:181], v[238:241], 0
	v_mfma_f32_16x16x32_bf16 v[80:83], v[186:189], v[238:241], 0
	v_mfma_f32_16x16x32_bf16 v[68:71], v[178:181], v[246:249], 0
	v_mfma_f32_16x16x32_bf16 v[64:67], v[186:189], v[246:249], 0
	v_mfma_f32_16x16x32_bf16 v[116:119], v[182:185], v[208:211], v[116:119]
	v_mfma_f32_16x16x32_bf16 v[112:115], v[200:203], v[208:211], v[112:115]
	v_mfma_f32_16x16x32_bf16 v[100:103], v[182:185], v[234:237], v[100:103]
	v_mfma_f32_16x16x32_bf16 v[96:99], v[200:203], v[234:237], v[96:99]
	v_mfma_f32_16x16x32_bf16 v[84:87], v[182:185], v[242:245], v[84:87]
	v_mfma_f32_16x16x32_bf16 v[80:83], v[200:203], v[242:245], v[80:83]
	v_mfma_f32_16x16x32_bf16 v[68:71], v[182:185], v[222:225], v[68:71]
	v_mfma_f32_16x16x32_bf16 v[64:67], v[200:203], v[222:225], v[64:67]
	s_barrier
	s_add_i32 s85, s85, s86
	s_mov_b32 m0, s85
	ds_read_b128 v[204:207], v199 offset:16384
	ds_read_b128 v[208:211], v199 offset:17408
	ds_read_b128 v[212:215], v199 offset:18432
	ds_read_b128 v[222:225], v199 offset:19456
	ds_read_b128 v[234:237], v199 offset:20480
	ds_read_b128 v[238:241], v199 offset:21504
	ds_read_b128 v[242:245], v199 offset:22528
	ds_read_b128 v[246:249], v199 offset:23552
	global_load_lds_dwordx4 v130, s[12:13]
	s_add_i32 m0, s85, 0x2000
	s_add_u32 s98, s12, 0x40000
	s_addc_u32 s99, s13, 0
	s_add_i32 s27, s27, s86
	global_load_lds_dwordx4 v134, s[12:13]
	s_mov_b32 m0, s27
	s_nop 0
	global_load_lds_dwordx4 v130, s[98:99]
	s_add_i32 m0, s27, 0x2000
	s_nop 0
	global_load_lds_dwordx4 v134, s[98:99]
	s_mov_b32 m0, s15
	s_nop 0
	global_load_lds_dwordx4 v128, s[42:43]
	s_mov_b32 m0, s87
	s_nop 0
	global_load_lds_dwordx4 v132, s[42:43]
	s_waitcnt vmcnt(8)
	s_waitcnt lgkmcnt(0)
	s_barrier
	s_waitcnt lgkmcnt(0)
	v_mfma_f32_16x16x32_bf16 v[60:63], v[150:153], v[204:207], 0
	v_mfma_f32_16x16x32_bf16 v[56:59], v[170:173], v[204:207], 0
	v_mfma_f32_16x16x32_bf16 v[44:47], v[150:153], v[212:215], 0
	v_mfma_f32_16x16x32_bf16 v[40:43], v[170:173], v[212:215], 0
	v_mfma_f32_16x16x32_bf16 v[28:31], v[150:153], v[234:237], 0
	v_mfma_f32_16x16x32_bf16 v[24:27], v[170:173], v[234:237], 0
	v_mfma_f32_16x16x32_bf16 v[12:15], v[150:153], v[242:245], 0
	v_mfma_f32_16x16x32_bf16 v[8:11], v[170:173], v[242:245], 0
	v_mfma_f32_16x16x32_bf16 v[60:63], v[154:157], v[208:211], v[60:63]
	v_mfma_f32_16x16x32_bf16 v[56:59], v[174:177], v[208:211], v[56:59]
	v_mfma_f32_16x16x32_bf16 v[44:47], v[154:157], v[222:225], v[44:47]
	v_mfma_f32_16x16x32_bf16 v[40:43], v[174:177], v[222:225], v[40:43]
	v_mfma_f32_16x16x32_bf16 v[28:31], v[154:157], v[238:241], v[28:31]
	v_mfma_f32_16x16x32_bf16 v[24:27], v[174:177], v[238:241], v[24:27]
	v_mfma_f32_16x16x32_bf16 v[12:15], v[154:157], v[246:249], v[12:15]
	v_mfma_f32_16x16x32_bf16 v[8:11], v[174:177], v[246:249], v[8:11]
	v_mfma_f32_16x16x32_bf16 v[52:55], v[178:181], v[204:207], 0
	v_mfma_f32_16x16x32_bf16 v[48:51], v[186:189], v[204:207], 0
	v_mfma_f32_16x16x32_bf16 v[36:39], v[178:181], v[212:215], 0
	v_mfma_f32_16x16x32_bf16 v[32:35], v[186:189], v[212:215], 0
	v_mfma_f32_16x16x32_bf16 v[20:23], v[178:181], v[234:237], 0
	v_mfma_f32_16x16x32_bf16 v[16:19], v[186:189], v[234:237], 0
	v_mfma_f32_16x16x32_bf16 v[4:7], v[178:181], v[242:245], 0
	v_mfma_f32_16x16x32_bf16 v[0:3], v[186:189], v[242:245], 0
	v_mfma_f32_16x16x32_bf16 v[52:55], v[182:185], v[208:211], v[52:55]
	v_mfma_f32_16x16x32_bf16 v[48:51], v[200:203], v[208:211], v[48:51]
	v_mfma_f32_16x16x32_bf16 v[36:39], v[182:185], v[222:225], v[36:39]
	v_mfma_f32_16x16x32_bf16 v[32:35], v[200:203], v[222:225], v[32:35]
	v_mfma_f32_16x16x32_bf16 v[20:23], v[182:185], v[238:241], v[20:23]
	v_mfma_f32_16x16x32_bf16 v[16:19], v[200:203], v[238:241], v[16:19]
	v_mfma_f32_16x16x32_bf16 v[4:7], v[182:185], v[246:249], v[4:7]
	v_mfma_f32_16x16x32_bf16 v[0:3], v[200:203], v[246:249], v[0:3]
	s_barrier
	s_add_i32 s27, 0, 0x18000
	v_add_u32_e32 v160, s27, v196
	s_add_i32 s85, 0, 0x1c000
	ds_read_b128 v[150:153], v160
	ds_read_b128 v[154:157], v160 offset:1024
	ds_read_b128 v[170:173], v160 offset:2048
	ds_read_b128 v[174:177], v160 offset:3072
	v_add_u32_e32 v160, s85, v196
	ds_read_b128 v[178:181], v160
	ds_read_b128 v[182:185], v160 offset:1024
	ds_read_b128 v[186:189], v160 offset:2048
	ds_read_b128 v[200:203], v160 offset:3072
	s_add_u32 s42, s42, 0x40000
	s_addc_u32 s43, s43, 0
	s_mov_b32 m0, s88
	ds_read_b128 v[204:207], v199 offset:32768
	ds_read_b128 v[208:211], v199 offset:33792
	ds_read_b128 v[212:215], v199 offset:34816
	ds_read_b128 v[222:225], v199 offset:35840
	ds_read_b128 v[234:237], v199 offset:36864
	ds_read_b128 v[238:241], v199 offset:37888
	ds_read_b128 v[242:245], v199 offset:38912
	ds_read_b128 v[246:249], v199 offset:39936
	global_load_lds_dwordx4 v128, s[42:43]
	s_mov_b32 m0, s89
	s_nop 0
	global_load_lds_dwordx4 v132, s[42:43]
	s_waitcnt vmcnt(8)
	s_waitcnt lgkmcnt(0)
	s_barrier
	s_waitcnt lgkmcnt(0)
	v_mfma_f32_16x16x32_bf16 v[124:127], v[150:153], v[204:207], v[124:127]
	v_mfma_f32_16x16x32_bf16 v[120:123], v[170:173], v[204:207], v[120:123]
	v_mfma_f32_16x16x32_bf16 v[108:111], v[150:153], v[212:215], v[108:111]
	v_mfma_f32_16x16x32_bf16 v[104:107], v[170:173], v[212:215], v[104:107]
	v_mfma_f32_16x16x32_bf16 v[92:95], v[150:153], v[234:237], v[92:95]
	v_mfma_f32_16x16x32_bf16 v[88:91], v[170:173], v[234:237], v[88:91]
	v_mfma_f32_16x16x32_bf16 v[76:79], v[150:153], v[242:245], v[76:79]
	v_mfma_f32_16x16x32_bf16 v[72:75], v[170:173], v[242:245], v[72:75]
	v_mfma_f32_16x16x32_bf16 v[124:127], v[154:157], v[208:211], v[124:127]
	v_mfma_f32_16x16x32_bf16 v[120:123], v[174:177], v[208:211], v[120:123]
	v_mfma_f32_16x16x32_bf16 v[108:111], v[154:157], v[222:225], v[108:111]
	v_mfma_f32_16x16x32_bf16 v[104:107], v[174:177], v[222:225], v[104:107]
	v_mfma_f32_16x16x32_bf16 v[92:95], v[154:157], v[238:241], v[92:95]
	v_mfma_f32_16x16x32_bf16 v[88:91], v[174:177], v[238:241], v[88:91]
	v_mfma_f32_16x16x32_bf16 v[76:79], v[154:157], v[246:249], v[76:79]
	v_mfma_f32_16x16x32_bf16 v[72:75], v[174:177], v[246:249], v[72:75]
	v_mfma_f32_16x16x32_bf16 v[116:119], v[178:181], v[204:207], v[116:119]
	v_mfma_f32_16x16x32_bf16 v[112:115], v[186:189], v[204:207], v[112:115]
	v_mfma_f32_16x16x32_bf16 v[100:103], v[178:181], v[212:215], v[100:103]
	v_mfma_f32_16x16x32_bf16 v[96:99], v[186:189], v[212:215], v[96:99]
	v_mfma_f32_16x16x32_bf16 v[84:87], v[178:181], v[234:237], v[84:87]
	v_mfma_f32_16x16x32_bf16 v[80:83], v[186:189], v[234:237], v[80:83]
	v_mfma_f32_16x16x32_bf16 v[68:71], v[178:181], v[242:245], v[68:71]
	v_mfma_f32_16x16x32_bf16 v[64:67], v[186:189], v[242:245], v[64:67]
	v_mfma_f32_16x16x32_bf16 v[116:119], v[182:185], v[208:211], v[116:119]
	v_mfma_f32_16x16x32_bf16 v[112:115], v[200:203], v[208:211], v[112:115]
	v_mfma_f32_16x16x32_bf16 v[100:103], v[182:185], v[222:225], v[100:103]
	v_mfma_f32_16x16x32_bf16 v[96:99], v[200:203], v[222:225], v[96:99]
	v_mfma_f32_16x16x32_bf16 v[84:87], v[182:185], v[238:241], v[84:87]
	v_mfma_f32_16x16x32_bf16 v[80:83], v[200:203], v[238:241], v[80:83]
	v_mfma_f32_16x16x32_bf16 v[68:71], v[182:185], v[246:249], v[68:71]
	v_mfma_f32_16x16x32_bf16 v[64:67], v[200:203], v[246:249], v[64:67]
	s_barrier
	s_add_i32 s27, s27, s86
	s_add_u32 s100, s12, 0x80
	s_addc_u32 s101, s13, 0
	s_mov_b32 m0, s27
	ds_read_b128 v[204:207], v199 offset:49152
	ds_read_b128 v[208:211], v199 offset:50176
	ds_read_b128 v[212:215], v199 offset:51200
	ds_read_b128 v[222:225], v199 offset:52224
	ds_read_b128 v[234:237], v199 offset:53248
	ds_read_b128 v[238:241], v199 offset:54272
	ds_read_b128 v[242:245], v199 offset:55296
	ds_read_b128 v[246:249], v199 offset:56320
	global_load_lds_dwordx4 v130, s[100:101]
	s_add_i32 m0, s27, 0x2000
	s_add_u32 s12, s12, 0x40080
	s_addc_u32 s13, s13, 0
	s_add_i32 s27, s85, s86
	global_load_lds_dwordx4 v134, s[100:101]
	s_mov_b32 m0, s27
	s_nop 0
	global_load_lds_dwordx4 v130, s[12:13]
	s_add_i32 m0, s27, 0x2000
	s_nop 0
	global_load_lds_dwordx4 v134, s[12:13]
	s_add_u32 s98, s42, 0xfffc0080
	s_addc_u32 s99, s43, -1
	s_mov_b32 m0, s92
	s_nop 0
	global_load_lds_dwordx4 v128, s[98:99]
	s_mov_b32 m0, s93
	s_nop 0
	global_load_lds_dwordx4 v132, s[98:99]
	s_waitcnt vmcnt(8)
	s_waitcnt lgkmcnt(0)
	s_barrier
	s_waitcnt lgkmcnt(0)
	v_mfma_f32_16x16x32_bf16 v[60:63], v[150:153], v[204:207], v[60:63]
	v_mfma_f32_16x16x32_bf16 v[56:59], v[170:173], v[204:207], v[56:59]
	v_mfma_f32_16x16x32_bf16 v[44:47], v[150:153], v[212:215], v[44:47]
	v_mfma_f32_16x16x32_bf16 v[40:43], v[170:173], v[212:215], v[40:43]
	v_mfma_f32_16x16x32_bf16 v[28:31], v[150:153], v[234:237], v[28:31]
	v_mfma_f32_16x16x32_bf16 v[24:27], v[170:173], v[234:237], v[24:27]
	v_mfma_f32_16x16x32_bf16 v[12:15], v[150:153], v[242:245], v[12:15]
	v_mfma_f32_16x16x32_bf16 v[8:11], v[170:173], v[242:245], v[8:11]
	v_mfma_f32_16x16x32_bf16 v[60:63], v[154:157], v[208:211], v[60:63]
	v_mfma_f32_16x16x32_bf16 v[56:59], v[174:177], v[208:211], v[56:59]
	v_mfma_f32_16x16x32_bf16 v[44:47], v[154:157], v[222:225], v[44:47]
	v_mfma_f32_16x16x32_bf16 v[40:43], v[174:177], v[222:225], v[40:43]
	v_mfma_f32_16x16x32_bf16 v[28:31], v[154:157], v[238:241], v[28:31]
	v_mfma_f32_16x16x32_bf16 v[24:27], v[174:177], v[238:241], v[24:27]
	v_mfma_f32_16x16x32_bf16 v[12:15], v[154:157], v[246:249], v[12:15]
	v_mfma_f32_16x16x32_bf16 v[8:11], v[174:177], v[246:249], v[8:11]
	v_mfma_f32_16x16x32_bf16 v[52:55], v[178:181], v[204:207], v[52:55]
	v_mfma_f32_16x16x32_bf16 v[48:51], v[186:189], v[204:207], v[48:51]
	v_mfma_f32_16x16x32_bf16 v[36:39], v[178:181], v[212:215], v[36:39]
	v_mfma_f32_16x16x32_bf16 v[32:35], v[186:189], v[212:215], v[32:35]
	v_mfma_f32_16x16x32_bf16 v[20:23], v[178:181], v[234:237], v[20:23]
	v_mfma_f32_16x16x32_bf16 v[16:19], v[186:189], v[234:237], v[16:19]
	v_mfma_f32_16x16x32_bf16 v[4:7], v[178:181], v[242:245], v[4:7]
	v_mfma_f32_16x16x32_bf16 v[0:3], v[186:189], v[242:245], v[0:3]
	v_mfma_f32_16x16x32_bf16 v[52:55], v[182:185], v[208:211], v[52:55]
	v_mfma_f32_16x16x32_bf16 v[48:51], v[200:203], v[208:211], v[48:51]
	v_mfma_f32_16x16x32_bf16 v[36:39], v[182:185], v[222:225], v[36:39]
	v_mfma_f32_16x16x32_bf16 v[32:35], v[200:203], v[222:225], v[32:35]
	v_mfma_f32_16x16x32_bf16 v[20:23], v[182:185], v[238:241], v[20:23]
	v_mfma_f32_16x16x32_bf16 v[16:19], v[200:203], v[238:241], v[16:19]
	v_mfma_f32_16x16x32_bf16 v[4:7], v[182:185], v[246:249], v[4:7]
	v_mfma_f32_16x16x32_bf16 v[0:3], v[200:203], v[246:249], v[0:3]
	s_barrier
	s_add_i32 s51, s51, 2
	s_add_u32 s40, s40, 0x100
	s_addc_u32 s41, s41, 0
	s_add_u32 s25, s25, 0x100
	s_addc_u32 s50, s50, 0
	s_cmp_gt_u32 s51, 13
.LBB0_478:
	s_add_u32 s12, s40, 0xfffc0080
	s_addc_u32 s13, s41, -1
	s_add_i32 s85, 0, 0x10000
	s_cmp_eq_u32 s51, 12
	s_cselect_b32 s43, s4, s13
	s_cselect_b32 s42, s9, s12
	v_add_u32_e32 v158, s85, v196
	s_cselect_b32 s13, s17, s50
	s_cselect_b32 s12, s24, s25
	s_add_i32 s27, 0, 0x14000
	ds_read_b128 v[150:153], v158
	ds_read_b128 v[154:157], v158 offset:1024
	ds_read_b128 v[170:173], v158 offset:2048
	ds_read_b128 v[174:177], v158 offset:3072
	v_add_u32_e32 v158, s27, v196
	ds_read_b128 v[178:181], v158
	ds_read_b128 v[182:185], v158 offset:1024
	ds_read_b128 v[186:189], v158 offset:2048
	ds_read_b128 v[200:203], v158 offset:3072
	s_add_i32 m0, s15, 0xc000
	ds_read_b128 v[204:207], v199
	ds_read_b128 v[208:211], v199 offset:1024
	ds_read_b128 v[212:215], v199 offset:2048
	ds_read_b128 v[234:237], v199 offset:3072
	ds_read_b128 v[238:241], v199 offset:4096
	ds_read_b128 v[242:245], v199 offset:5120
	ds_read_b128 v[246:249], v199 offset:6144
	ds_read_b128 v[222:225], v199 offset:7168
	global_load_lds_dwordx4 v146, s[40:41]
	s_add_i32 m0, s15, 0xe000
	s_nop 0
	global_load_lds_dwordx4 v148, s[40:41]
	s_waitcnt vmcnt(8)
	s_waitcnt lgkmcnt(0)
	s_barrier
	s_waitcnt lgkmcnt(0)
	v_mfma_f32_16x16x32_bf16 v[124:127], v[150:153], v[204:207], v[124:127]
	v_mfma_f32_16x16x32_bf16 v[120:123], v[170:173], v[204:207], v[120:123]
	v_mfma_f32_16x16x32_bf16 v[108:111], v[150:153], v[212:215], v[108:111]
	v_mfma_f32_16x16x32_bf16 v[104:107], v[170:173], v[212:215], v[104:107]
	v_mfma_f32_16x16x32_bf16 v[92:95], v[150:153], v[238:241], v[92:95]
	v_mfma_f32_16x16x32_bf16 v[88:91], v[170:173], v[238:241], v[88:91]
	v_mfma_f32_16x16x32_bf16 v[76:79], v[150:153], v[246:249], v[76:79]
	v_mfma_f32_16x16x32_bf16 v[72:75], v[170:173], v[246:249], v[72:75]
	v_mfma_f32_16x16x32_bf16 v[124:127], v[154:157], v[208:211], v[124:127]
	v_mfma_f32_16x16x32_bf16 v[120:123], v[174:177], v[208:211], v[120:123]
	v_mfma_f32_16x16x32_bf16 v[108:111], v[154:157], v[234:237], v[108:111]
	v_mfma_f32_16x16x32_bf16 v[104:107], v[174:177], v[234:237], v[104:107]
	v_mfma_f32_16x16x32_bf16 v[92:95], v[154:157], v[242:245], v[92:95]
	v_mfma_f32_16x16x32_bf16 v[88:91], v[174:177], v[242:245], v[88:91]
	v_mfma_f32_16x16x32_bf16 v[76:79], v[154:157], v[222:225], v[76:79]
	v_mfma_f32_16x16x32_bf16 v[72:75], v[174:177], v[222:225], v[72:75]
	v_mfma_f32_16x16x32_bf16 v[116:119], v[178:181], v[204:207], v[116:119]
	v_mfma_f32_16x16x32_bf16 v[112:115], v[186:189], v[204:207], v[112:115]
	v_mfma_f32_16x16x32_bf16 v[100:103], v[178:181], v[212:215], v[100:103]
	v_mfma_f32_16x16x32_bf16 v[96:99], v[186:189], v[212:215], v[96:99]
	v_mfma_f32_16x16x32_bf16 v[84:87], v[178:181], v[238:241], v[84:87]
	v_mfma_f32_16x16x32_bf16 v[80:83], v[186:189], v[238:241], v[80:83]
	v_mfma_f32_16x16x32_bf16 v[68:71], v[178:181], v[246:249], v[68:71]
	v_mfma_f32_16x16x32_bf16 v[64:67], v[186:189], v[246:249], v[64:67]
	v_mfma_f32_16x16x32_bf16 v[116:119], v[182:185], v[208:211], v[116:119]
	v_mfma_f32_16x16x32_bf16 v[112:115], v[200:203], v[208:211], v[112:115]
	v_mfma_f32_16x16x32_bf16 v[100:103], v[182:185], v[234:237], v[100:103]
	v_mfma_f32_16x16x32_bf16 v[96:99], v[200:203], v[234:237], v[96:99]
	v_mfma_f32_16x16x32_bf16 v[84:87], v[182:185], v[242:245], v[84:87]
	v_mfma_f32_16x16x32_bf16 v[80:83], v[200:203], v[242:245], v[80:83]
	v_mfma_f32_16x16x32_bf16 v[68:71], v[182:185], v[222:225], v[68:71]
	v_mfma_f32_16x16x32_bf16 v[64:67], v[200:203], v[222:225], v[64:67]
	s_barrier
	s_add_i32 s85, s85, s86
	s_mov_b32 m0, s85
	ds_read_b128 v[204:207], v199 offset:16384
	ds_read_b128 v[208:211], v199 offset:17408
	ds_read_b128 v[212:215], v199 offset:18432
	ds_read_b128 v[222:225], v199 offset:19456
	ds_read_b128 v[234:237], v199 offset:20480
	ds_read_b128 v[238:241], v199 offset:21504
	ds_read_b128 v[242:245], v199 offset:22528
	ds_read_b128 v[246:249], v199 offset:23552
	global_load_lds_dwordx4 v130, s[12:13]
	s_add_i32 m0, s85, 0x2000
	s_add_u32 s98, s12, 0x40000
	s_addc_u32 s99, s13, 0
	s_add_i32 s27, s27, s86
	global_load_lds_dwordx4 v134, s[12:13]
	s_mov_b32 m0, s27
	s_nop 0
	global_load_lds_dwordx4 v130, s[98:99]
	s_add_i32 m0, s27, 0x2000
	s_nop 0
	global_load_lds_dwordx4 v134, s[98:99]
	s_mov_b32 m0, s15
	s_nop 0
	global_load_lds_dwordx4 v128, s[42:43]
	s_mov_b32 m0, s87
	s_nop 0
	global_load_lds_dwordx4 v132, s[42:43]
	s_waitcnt vmcnt(8)
	s_waitcnt lgkmcnt(0)
	s_barrier
	s_waitcnt lgkmcnt(0)
	v_mfma_f32_16x16x32_bf16 v[60:63], v[150:153], v[204:207], v[60:63]
	v_mfma_f32_16x16x32_bf16 v[56:59], v[170:173], v[204:207], v[56:59]
	v_mfma_f32_16x16x32_bf16 v[44:47], v[150:153], v[212:215], v[44:47]
	v_mfma_f32_16x16x32_bf16 v[40:43], v[170:173], v[212:215], v[40:43]
	v_mfma_f32_16x16x32_bf16 v[28:31], v[150:153], v[234:237], v[28:31]
	v_mfma_f32_16x16x32_bf16 v[24:27], v[170:173], v[234:237], v[24:27]
	v_mfma_f32_16x16x32_bf16 v[12:15], v[150:153], v[242:245], v[12:15]
	v_mfma_f32_16x16x32_bf16 v[8:11], v[170:173], v[242:245], v[8:11]
	v_mfma_f32_16x16x32_bf16 v[60:63], v[154:157], v[208:211], v[60:63]
	v_mfma_f32_16x16x32_bf16 v[56:59], v[174:177], v[208:211], v[56:59]
	v_mfma_f32_16x16x32_bf16 v[44:47], v[154:157], v[222:225], v[44:47]
	v_mfma_f32_16x16x32_bf16 v[40:43], v[174:177], v[222:225], v[40:43]
	v_mfma_f32_16x16x32_bf16 v[28:31], v[154:157], v[238:241], v[28:31]
	v_mfma_f32_16x16x32_bf16 v[24:27], v[174:177], v[238:241], v[24:27]
	v_mfma_f32_16x16x32_bf16 v[12:15], v[154:157], v[246:249], v[12:15]
	v_mfma_f32_16x16x32_bf16 v[8:11], v[174:177], v[246:249], v[8:11]
	v_mfma_f32_16x16x32_bf16 v[52:55], v[178:181], v[204:207], v[52:55]
	v_mfma_f32_16x16x32_bf16 v[48:51], v[186:189], v[204:207], v[48:51]
	v_mfma_f32_16x16x32_bf16 v[36:39], v[178:181], v[212:215], v[36:39]
	v_mfma_f32_16x16x32_bf16 v[32:35], v[186:189], v[212:215], v[32:35]
	v_mfma_f32_16x16x32_bf16 v[20:23], v[178:181], v[234:237], v[20:23]
	v_mfma_f32_16x16x32_bf16 v[16:19], v[186:189], v[234:237], v[16:19]
	v_mfma_f32_16x16x32_bf16 v[4:7], v[178:181], v[242:245], v[4:7]
	v_mfma_f32_16x16x32_bf16 v[0:3], v[186:189], v[242:245], v[0:3]
	v_mfma_f32_16x16x32_bf16 v[52:55], v[182:185], v[208:211], v[52:55]
	v_mfma_f32_16x16x32_bf16 v[48:51], v[200:203], v[208:211], v[48:51]
	v_mfma_f32_16x16x32_bf16 v[36:39], v[182:185], v[222:225], v[36:39]
	v_mfma_f32_16x16x32_bf16 v[32:35], v[200:203], v[222:225], v[32:35]
	v_mfma_f32_16x16x32_bf16 v[20:23], v[182:185], v[238:241], v[20:23]
	v_mfma_f32_16x16x32_bf16 v[16:19], v[200:203], v[238:241], v[16:19]
	v_mfma_f32_16x16x32_bf16 v[4:7], v[182:185], v[246:249], v[4:7]
	v_mfma_f32_16x16x32_bf16 v[0:3], v[200:203], v[246:249], v[0:3]
	s_barrier
	s_add_i32 s27, 0, 0x18000
	v_add_u32_e32 v160, s27, v196
	s_add_i32 s85, 0, 0x1c000
	ds_read_b128 v[150:153], v160
	ds_read_b128 v[154:157], v160 offset:1024
	ds_read_b128 v[170:173], v160 offset:2048
	ds_read_b128 v[174:177], v160 offset:3072
	v_add_u32_e32 v160, s85, v196
	ds_read_b128 v[178:181], v160
	ds_read_b128 v[182:185], v160 offset:1024
	ds_read_b128 v[186:189], v160 offset:2048
	ds_read_b128 v[200:203], v160 offset:3072
	s_add_u32 s42, s42, 0x40000
	s_addc_u32 s43, s43, 0
	s_mov_b32 m0, s88
	ds_read_b128 v[204:207], v199 offset:32768
	ds_read_b128 v[208:211], v199 offset:33792
	ds_read_b128 v[212:215], v199 offset:34816
	ds_read_b128 v[222:225], v199 offset:35840
	ds_read_b128 v[234:237], v199 offset:36864
	ds_read_b128 v[238:241], v199 offset:37888
	ds_read_b128 v[242:245], v199 offset:38912
	ds_read_b128 v[246:249], v199 offset:39936
	global_load_lds_dwordx4 v128, s[42:43]
	s_mov_b32 m0, s89
	s_nop 0
	global_load_lds_dwordx4 v132, s[42:43]
	s_waitcnt vmcnt(8)
	s_waitcnt lgkmcnt(0)
	s_barrier
	s_waitcnt lgkmcnt(0)
	v_mfma_f32_16x16x32_bf16 v[124:127], v[150:153], v[204:207], v[124:127]
	v_mfma_f32_16x16x32_bf16 v[120:123], v[170:173], v[204:207], v[120:123]
	v_mfma_f32_16x16x32_bf16 v[108:111], v[150:153], v[212:215], v[108:111]
	v_mfma_f32_16x16x32_bf16 v[104:107], v[170:173], v[212:215], v[104:107]
	v_mfma_f32_16x16x32_bf16 v[92:95], v[150:153], v[234:237], v[92:95]
	v_mfma_f32_16x16x32_bf16 v[88:91], v[170:173], v[234:237], v[88:91]
	v_mfma_f32_16x16x32_bf16 v[76:79], v[150:153], v[242:245], v[76:79]
	v_mfma_f32_16x16x32_bf16 v[72:75], v[170:173], v[242:245], v[72:75]
	v_mfma_f32_16x16x32_bf16 v[124:127], v[154:157], v[208:211], v[124:127]
	v_mfma_f32_16x16x32_bf16 v[120:123], v[174:177], v[208:211], v[120:123]
	v_mfma_f32_16x16x32_bf16 v[108:111], v[154:157], v[222:225], v[108:111]
	v_mfma_f32_16x16x32_bf16 v[104:107], v[174:177], v[222:225], v[104:107]
	v_mfma_f32_16x16x32_bf16 v[92:95], v[154:157], v[238:241], v[92:95]
	v_mfma_f32_16x16x32_bf16 v[88:91], v[174:177], v[238:241], v[88:91]
	v_mfma_f32_16x16x32_bf16 v[76:79], v[154:157], v[246:249], v[76:79]
	v_mfma_f32_16x16x32_bf16 v[72:75], v[174:177], v[246:249], v[72:75]
	v_mfma_f32_16x16x32_bf16 v[116:119], v[178:181], v[204:207], v[116:119]
	v_mfma_f32_16x16x32_bf16 v[112:115], v[186:189], v[204:207], v[112:115]
	v_mfma_f32_16x16x32_bf16 v[100:103], v[178:181], v[212:215], v[100:103]
	v_mfma_f32_16x16x32_bf16 v[96:99], v[186:189], v[212:215], v[96:99]
	v_mfma_f32_16x16x32_bf16 v[84:87], v[178:181], v[234:237], v[84:87]
	v_mfma_f32_16x16x32_bf16 v[80:83], v[186:189], v[234:237], v[80:83]
	v_mfma_f32_16x16x32_bf16 v[68:71], v[178:181], v[242:245], v[68:71]
	v_mfma_f32_16x16x32_bf16 v[64:67], v[186:189], v[242:245], v[64:67]
	v_mfma_f32_16x16x32_bf16 v[116:119], v[182:185], v[208:211], v[116:119]
	v_mfma_f32_16x16x32_bf16 v[112:115], v[200:203], v[208:211], v[112:115]
	v_mfma_f32_16x16x32_bf16 v[100:103], v[182:185], v[222:225], v[100:103]
	v_mfma_f32_16x16x32_bf16 v[96:99], v[200:203], v[222:225], v[96:99]
	v_mfma_f32_16x16x32_bf16 v[84:87], v[182:185], v[238:241], v[84:87]
	v_mfma_f32_16x16x32_bf16 v[80:83], v[200:203], v[238:241], v[80:83]
	v_mfma_f32_16x16x32_bf16 v[68:71], v[182:185], v[246:249], v[68:71]
	v_mfma_f32_16x16x32_bf16 v[64:67], v[200:203], v[246:249], v[64:67]
	s_barrier
	s_add_i32 s27, s27, s86
	s_add_u32 s100, s12, 0x80
	s_addc_u32 s101, s13, 0
	s_mov_b32 m0, s27
	ds_read_b128 v[204:207], v199 offset:49152
	ds_read_b128 v[208:211], v199 offset:50176
	ds_read_b128 v[212:215], v199 offset:51200
	ds_read_b128 v[222:225], v199 offset:52224
	ds_read_b128 v[234:237], v199 offset:53248
	ds_read_b128 v[238:241], v199 offset:54272
	ds_read_b128 v[242:245], v199 offset:55296
	ds_read_b128 v[246:249], v199 offset:56320
	global_load_lds_dwordx4 v130, s[100:101]
	s_add_i32 m0, s27, 0x2000
	s_add_u32 s12, s12, 0x40080
	s_addc_u32 s13, s13, 0
	s_add_i32 s27, s85, s86
	global_load_lds_dwordx4 v134, s[100:101]
	s_mov_b32 m0, s27
	s_nop 0
	global_load_lds_dwordx4 v130, s[12:13]
	s_add_i32 m0, s27, 0x2000
	s_nop 0
	global_load_lds_dwordx4 v134, s[12:13]
	s_add_u32 s98, s42, 0xfffc0080
	s_addc_u32 s99, s43, -1
	s_mov_b32 m0, s92
	s_nop 0
	global_load_lds_dwordx4 v128, s[98:99]
	s_mov_b32 m0, s93
	s_nop 0
	global_load_lds_dwordx4 v132, s[98:99]
	s_waitcnt vmcnt(8)
	s_waitcnt lgkmcnt(0)
	s_barrier
	s_waitcnt lgkmcnt(0)
	v_mfma_f32_16x16x32_bf16 v[60:63], v[150:153], v[204:207], v[60:63]
	v_mfma_f32_16x16x32_bf16 v[56:59], v[170:173], v[204:207], v[56:59]
	v_mfma_f32_16x16x32_bf16 v[44:47], v[150:153], v[212:215], v[44:47]
	v_mfma_f32_16x16x32_bf16 v[40:43], v[170:173], v[212:215], v[40:43]
	v_mfma_f32_16x16x32_bf16 v[28:31], v[150:153], v[234:237], v[28:31]
	v_mfma_f32_16x16x32_bf16 v[24:27], v[170:173], v[234:237], v[24:27]
	v_mfma_f32_16x16x32_bf16 v[12:15], v[150:153], v[242:245], v[12:15]
	v_mfma_f32_16x16x32_bf16 v[8:11], v[170:173], v[242:245], v[8:11]
	v_mfma_f32_16x16x32_bf16 v[60:63], v[154:157], v[208:211], v[60:63]
	v_mfma_f32_16x16x32_bf16 v[56:59], v[174:177], v[208:211], v[56:59]
	v_mfma_f32_16x16x32_bf16 v[44:47], v[154:157], v[222:225], v[44:47]
	v_mfma_f32_16x16x32_bf16 v[40:43], v[174:177], v[222:225], v[40:43]
	v_mfma_f32_16x16x32_bf16 v[28:31], v[154:157], v[238:241], v[28:31]
	v_mfma_f32_16x16x32_bf16 v[24:27], v[174:177], v[238:241], v[24:27]
	v_mfma_f32_16x16x32_bf16 v[12:15], v[154:157], v[246:249], v[12:15]
	v_mfma_f32_16x16x32_bf16 v[8:11], v[174:177], v[246:249], v[8:11]
	v_mfma_f32_16x16x32_bf16 v[52:55], v[178:181], v[204:207], v[52:55]
	v_mfma_f32_16x16x32_bf16 v[48:51], v[186:189], v[204:207], v[48:51]
	v_mfma_f32_16x16x32_bf16 v[36:39], v[178:181], v[212:215], v[36:39]
	v_mfma_f32_16x16x32_bf16 v[32:35], v[186:189], v[212:215], v[32:35]
	v_mfma_f32_16x16x32_bf16 v[20:23], v[178:181], v[234:237], v[20:23]
	v_mfma_f32_16x16x32_bf16 v[16:19], v[186:189], v[234:237], v[16:19]
	v_mfma_f32_16x16x32_bf16 v[4:7], v[178:181], v[242:245], v[4:7]
	v_mfma_f32_16x16x32_bf16 v[0:3], v[186:189], v[242:245], v[0:3]
	v_mfma_f32_16x16x32_bf16 v[52:55], v[182:185], v[208:211], v[52:55]
	v_mfma_f32_16x16x32_bf16 v[48:51], v[200:203], v[208:211], v[48:51]
	v_mfma_f32_16x16x32_bf16 v[36:39], v[182:185], v[222:225], v[36:39]
	v_mfma_f32_16x16x32_bf16 v[32:35], v[200:203], v[222:225], v[32:35]
	v_mfma_f32_16x16x32_bf16 v[20:23], v[182:185], v[238:241], v[20:23]
	v_mfma_f32_16x16x32_bf16 v[16:19], v[200:203], v[238:241], v[16:19]
	v_mfma_f32_16x16x32_bf16 v[4:7], v[182:185], v[246:249], v[4:7]
	v_mfma_f32_16x16x32_bf16 v[0:3], v[200:203], v[246:249], v[0:3]
	s_barrier
	s_add_i32 s51, s51, 2
	s_add_u32 s40, s40, 0x100
	s_addc_u32 s41, s41, 0
	s_add_u32 s25, s25, 0x100
	s_addc_u32 s50, s50, 0
	s_cmp_gt_u32 s51, 13
	s_cbranch_scc0 .LBB0_478
	s_and_b64 vcc, exec, s[10:11]
	s_cbranch_vccz .LBB0_481
	s_barrier

.LBB0_616:
	s_setprio 0
	s_waitcnt vmcnt(0)
	v_readlane_b32 s90, v255, 19
	v_readlane_b32 s68, v254, 44
	s_mov_b64 s[94:95], s[20:21]
	v_readlane_b32 s88, v254, 60
	v_readlane_b32 s20, v255, 17
	v_readlane_b32 s91, v255, 20
	v_readlane_b32 s86, v255, 21
	v_readlane_b32 s84, v255, 23
	v_readlane_b32 s69, v254, 45
	v_readlane_b32 s70, v254, 46
	v_readlane_b32 s71, v254, 47
	v_readlane_b32 s72, v254, 48
	v_readlane_b32 s73, v254, 49
	v_readlane_b32 s74, v254, 50
	v_readlane_b32 s75, v254, 51
	v_readlane_b32 s76, v254, 52
	v_readlane_b32 s77, v254, 53
	v_readlane_b32 s78, v254, 54
	v_readlane_b32 s79, v254, 55
	v_readlane_b32 s80, v254, 56
	v_readlane_b32 s81, v254, 57
	v_readlane_b32 s82, v254, 58
	v_readlane_b32 s83, v254, 59
	v_readlane_b32 s89, v254, 61
	v_readlane_b32 s93, v255, 14
	v_readlane_b32 s21, v255, 18
	v_readlane_b32 s87, v255, 22
	v_readlane_b32 s85, v255, 24
	v_readlane_b32 s91, v255, 27
	v_readlane_b32 s92, v255, 28
	s_mov_b32 s28, 0x3fb8aa3b
	s_barrier
